# v16: v15 + dilation-16 row masks recomputed in place (v_cmp from two kept thresholds) instead of v_writelane spills / v_readlane read-backs
# speedup vs baseline: 1.0094x; 1.0094x over previous
; template <int MIX, bool DRY = false>
; __device__ __forceinline__ void attn_phase(LAS unsigned char* lds, const bf16_t* Qb, const bf16_t* Kb, const bf16_t* Vb, bf16_t* Gb, const float* qg, const float* kg, const float* sinks) {
;     ...
;             constexpr int g = 2, dil = 16;
;             const bf16_t* Qg = Qb + (size_t)g * NTOK * 1024;
;             const bf16_t* Kg = Kb + (size_t)g * NTOK * KVW + kvh * 64;
;             const bf16_t* Vg = Vb + (size_t)g * NTOK * KVW + kvh * 64;
; #pragma unroll 1
;             for (int task = wave; task < 16; task += 8) {
;                 const int res = task, hr = r >> 3, qi = r & 7, tl = res + 16 * qi, f0 = t0 >> 4, head = kvh * REP + hr;
;                 const float negM2 = -Mb * LOG2E;
;                 const bf16_t* qptr = Qg + (rowb + t0 + tl) * 1024 + head * 64 + 8 * h;
;                 bf16x8 qf[4];
; #pragma unroll
;                 for (int s = 0; s < 4; ++s) qf[s] = *(const bf16x8*)(qptr + 16 * s);
;                 const long kstep = (long)32 * dil * KVW, vstep8 = (long)8 * dil * KVW;
;                 const bf16_t* kp = Kg + (rowb + res + (long)dil * (f0 - 128 + vkey)) * KVW + 8 * vchunk;
;                 const bf16_t* vp = Vg + (rowb + res + (long)dil * (f0 - 128 + vkey)) * KVW + 8 * vchunk;
;                 f32x16 O0, O1, Lr;
; #pragma unroll
;                 for (int i = 0; i < 16; ++i) { O0[i] = 0.f; O1[i] = 0.f; Lr[i] = 0.f; }
;                 float lsum_v = 0.f; (void)lsum_v;
;                 bf16x8 kb[3][4]; u32x4 vb[3][4];
; #pragma unroll
;                 for (int t = 0; t < 3; ++t) {
; #pragma unroll
;                     for (int s = 0; s < 4; ++s) kb[t][s] = *(const bf16x8*)(kp + t * kstep + s * vstep8);
; #pragma unroll
;                     for (int j = 0; j < 4; ++j) vb[t][j] = *(const u32x4*)(vp + t * kstep + j * vstep8);
;                 }
.LBB0_463:
	s_andn2_b64 vcc, exec, s[4:5]
	s_cbranch_vccnz .LBB0_469
	v_mul_u32_u24_e32 v17, 0x90, v216
	v_lshlrev_b32_e32 v18, 5, v195
	v_add3_u32 v22, s33, v17, v18
	v_lshrrev_b32_e32 v18, 2, v191
	v_lshrrev_b32_e32 v17, 4, v191
	v_bitop3_b32 v25, v217, v18, 4 bitop3:0x78
	v_xor_b32_e32 v26, v25, v17
	v_xor_b32_e32 v17, v17, v203
	v_and_b32_e32 v18, 4, v18
	v_lshrrev_b32_e32 v16, 3, v191
	v_bitop3_b32 v17, v17, v18, 7 bitop3:0x6c
	v_lshlrev_b32_e32 v29, 4, v17
	v_or_b32_e32 v17, 24, v16
	v_lshl_add_u32 v30, v17, 7, s33
	v_lshrrev_b32_e32 v17, 1, v17
	s_lshl_b32 s14, s20, 3
	v_mov_b32_e32 v21, s33
	s_movk_i32 s4, 0x90
	v_xor_b32_e32 v17, v17, v203
	v_mad_u32_u24 v21, v16, s4, v21
	v_bitop3_b32 v17, v17, v18, 7 bitop3:0x6c
	s_sub_i32 s4, 0x80, s14
	v_lshlrev_b32_e32 v31, 4, v17
	v_max_i32_e32 v17, s4, v217
	v_sub_u32_e32 v17, v17, v192
	v_mov_b32_e32 v248, v17
	s_lshl_b32 s91, s21, 8
	s_sub_i32 s6, 64, s14
	s_sub_i32 s20, 32, s14
	v_lshl_add_u32 v24, v16, 7, s33
	v_or_b32_e32 v27, 8, v16
	v_lshl_or_b32 v16, s18, 3, v16
	s_waitcnt vmcnt(3)
	v_lshlrev_b32_e32 v184, 4, v217
	v_lshrrev_b32_e32 v19, 3, v193
	v_and_b32_e32 v18, 32, v203
	v_lshrrev_b32_e32 v18, 1, v18
	v_lshl_add_u32 v28, v27, 7, s33
	v_lshrrev_b32_e32 v27, 1, v27
	v_lshlrev_b32_e32 v216, 2, v19
	v_xor_b32_e32 v25, v25, v27
	v_lshlrev_b32_e32 v20, 3, v194
	v_sub_u32_e32 v23, v217, v192
	v_lshlrev_b32_e32 v26, 4, v26
	v_lshlrev_b32_e32 v25, 4, v25
	v_add_u32_e32 v27, 0x800, v24
	v_mov_b64_e32 v[182:183], v[112:113]
	v_mov_b32_e32 v185, v113
	v_add_u32_e32 v220, v24, v26
	v_add_u32_e32 v221, v28, v25
	v_add_u32_e32 v222, v27, v29
	v_add_u32_e32 v223, v30, v31
	v_add_u32_e32 v224, v21, v184
	v_add_u32_e32 v225, v22, v20
	v_readlane_b32 s92, v251, 62
	s_mov_b64 s[88:89], s[36:37]
	v_cmp_gt_i32_e64 s[72:73], 2, v23
	v_cmp_gt_i32_e64 s[74:75], 3, v23
	v_cmp_gt_i32_e64 s[76:77], 0, v23
	v_cmp_gt_i32_e64 s[78:79], 1, v23
	v_or_b32_e32 v17, 0xffffffe0, v217
	s_sub_i32 s4, 0x60, s14
	v_max_i32_e32 v17, s4, v17
	v_sub_u32_e32 v17, v17, v192
	v_mov_b32_e32 v249, v17
	v_readlane_b32 s14, v251, 63
	s_add_u32 s16, s14, s12
	v_cmp_lt_i32_e64 s[96:97], 24, v17
	v_cmp_lt_i32_e64 s[98:99], 25, v17
	v_cmp_lt_i32_e64 s[80:81], 26, v17
	v_cmp_lt_i32_e64 s[4:5], 27, v17
	v_readlane_b32 s15, v250, 0
	s_addc_u32 s17, s15, s13
	s_lshl_b32 s14, s19, 8
	v_or_b32_e32 v17, 0xffffffc0, v217
	v_subrev_u32_e32 v16, s14, v16
	v_max_i32_e32 v17, s6, v17
	v_add_u32_e32 v16, 0xffffff80, v16
	v_sub_u32_e32 v32, v17, v192
	v_ashrrev_i32_e32 v17, 31, v16
	v_lshlrev_b64 v[16:17], 12, v[16:17]
	s_add_u32 s0, s94, s0
	v_lshl_add_u64 v[16:17], s[16:17], 0, v[16:17]
	s_addc_u32 s1, s95, s1
	v_lshl_add_u64 v[190:191], v[16:17], 1, s[0:1]
	v_or_b32_e32 v16, 0xffffffa0, v217
	v_max_i32_e32 v16, s20, v16
	v_sub_u32_e32 v33, v16, v192
	v_add_u32_e32 v16, s36, v184
	v_lshl_add_u32 v17, v19, 7, v16
	v_lshl_add_u32 v218, v17, 2, v201
	v_lshlrev_b32_e32 v219, 7, v17
	v_ashrrev_i32_e32 v17, 31, v16
	v_lshl_add_u64 v[16:17], s[82:83], 0, v[16:17]
	v_lshlrev_b64 v[16:17], 11, v[16:17]
	v_or_b32_e32 v16, v16, v18
	v_lshl_or_b32 v18, v19, 6, s91
	v_ashrrev_i32_e32 v19, 31, v18
	v_readlane_b32 s0, v251, 24
	v_lshl_add_u64 v[16:17], v[18:19], 1, v[16:17]
	v_readlane_b32 s1, v251, 25
	v_cmp_lt_i32_e64 s[6:7], 0, v32
	v_cmp_lt_i32_e64 s[8:9], 1, v32
	v_cmp_lt_i32_e64 s[10:11], 2, v32
	v_cmp_lt_i32_e64 s[12:13], 3, v32
	v_cmp_lt_i32_e64 s[14:15], 8, v32
	v_cmp_lt_i32_e64 s[16:17], 9, v32
	v_cmp_lt_i32_e64 s[18:19], 10, v32
	v_lshl_add_u64 v[192:193], s[0:1], 0, v[16:17]
	v_cmp_lt_i32_e64 s[20:21], 11, v32
	v_cmp_lt_i32_e64 s[22:23], 16, v32
	v_cmp_lt_i32_e64 s[24:25], 17, v32
	v_cmp_lt_i32_e64 s[26:27], 18, v32
	v_cmp_lt_i32_e64 s[28:29], 19, v32
	v_cmp_lt_i32_e64 s[30:31], 24, v32
	v_cmp_lt_i32_e64 s[34:35], 25, v32
	v_cmp_lt_i32_e64 s[0:1], 26, v32
	v_cmp_lt_i32_e64 s[36:37], 27, v32
	v_cmp_lt_i32_e64 s[40:41], 0, v33
	v_cmp_lt_i32_e64 s[42:43], 1, v33
	v_cmp_lt_i32_e64 s[44:45], 2, v33
	v_cmp_lt_i32_e64 s[46:47], 3, v33
	v_cmp_lt_i32_e64 s[48:49], 8, v33
	v_cmp_lt_i32_e64 s[50:51], 9, v33
	v_cmp_lt_i32_e64 s[52:53], 10, v33
	v_cmp_lt_i32_e64 s[54:55], 11, v33
	v_cmp_lt_i32_e64 s[56:57], 16, v33
	v_cmp_lt_i32_e64 s[58:59], 17, v33
	v_cmp_lt_i32_e64 s[60:61], 18, v33
	v_cmp_lt_i32_e64 s[62:63], 19, v33
	v_cmp_lt_i32_e64 s[64:65], 24, v33
	v_cmp_lt_i32_e64 s[66:67], 25, v33
	v_cmp_lt_i32_e64 s[68:69], 26, v33
	v_cmp_lt_i32_e64 s[70:71], 27, v33
	s_branch .LBB0_466

; #define STAGE_K_D(T) { _Pragma("unroll") for (int j = 0; j < ((T) == 4 ? 1 : 4); ++j) *(LAS bf16x8*)(kwv + (8 * j + vkey) * 128 + ((vchunk ^ ST_SW(8 * j + vkey)) << 4)) = kb[(T) % 3][j]; }
; template <int MIX, bool DRY = false>
; __device__ __forceinline__ void attn_phase(LAS unsigned char* lds, const bf16_t* Qb, const bf16_t* Kb, const bf16_t* Vb, bf16_t* Gb, const float* qg, const float* kg, const float* sinks) {
;     ...
;             for (int task = wave; task < 16; task += 8) {
;                 const int res = task, hr = r >> 3, qi = r & 7, tl = res + 16 * qi, f0 = t0 >> 4, head = kvh * REP + hr;
;                 const float negM2 = -Mb * LOG2E;
;                 const bf16_t* qptr = Qg + (rowb + t0 + tl) * 1024 + head * 64 + 8 * h;
;                 bf16x8 qf[4];
; #pragma unroll
;                 for (int s = 0; s < 4; ++s) qf[s] = *(const bf16x8*)(qptr + 16 * s);
;                 const long kstep = (long)32 * dil * KVW, vstep8 = (long)8 * dil * KVW;
;                 const bf16_t* kp = Kg + (rowb + res + (long)dil * (f0 - 128 + vkey)) * KVW + 8 * vchunk;
;                 const bf16_t* vp = Vg + (rowb + res + (long)dil * (f0 - 128 + vkey)) * KVW + 8 * vchunk;
;                 f32x16 O0, O1, Lr;
; #pragma unroll
;                 for (int i = 0; i < 16; ++i) { O0[i] = 0.f; O1[i] = 0.f; Lr[i] = 0.f; }
;                 float lsum_v = 0.f; (void)lsum_v;
;                 bf16x8 kb[3][4]; u32x4 vb[3][4];
; #pragma unroll
;                 for (int t = 0; t < 3; ++t) {
; #pragma unroll
;                     for (int s = 0; s < 4; ++s) kb[t][s] = *(const bf16x8*)(kp + t * kstep + s * vstep8);
; #pragma unroll
;                     for (int j = 0; j < 4; ++j) vb[t][j] = *(const u32x4*)(vp + t * kstep + j * vstep8);
;                 }
;                 __builtin_amdgcn_sched_barrier(0);
;     ...
;                 f32x16 S2[2];
;                 STAGE_K_D(0) ATT_QK(S2[0], GETK_D)
; #pragma unroll
;                 for (int kt = 0; kt < 5; ++kt) {
;                     const int kf0 = f0 - 128 + 32 * kt;
;                     if (kt < 4) { STAGE_K_D(kt + 1) ATT_QK(S2[(kt + 1) & 1], GETK_D) }
;     ...
;                     ATT_SMPV(kt, S2[kt & 1], kf0, qi, md, GETV_D, true, true, true)
.LBB0_466:
	v_lshl_add_u64 v[194:195], v[190:191], 0, v[184:185]
	v_add_co_u32_e32 v16, vcc, 0x14a00000, v194
	global_load_dwordx4 v[108:111], v[192:193], off offset:-64
	global_load_dwordx4 v[104:107], v[192:193], off offset:-32
	global_load_dwordx4 v[100:103], v[192:193], off
	global_load_dwordx4 v[96:99], v[192:193], off offset:32
	v_addc_co_u32_e32 v17, vcc, 0, v195, vcc
	v_add_co_u32_e32 v20, vcc, 0x14a10000, v194
	v_add_u32_e32 v226, s88, v184
	s_nop 0
	v_addc_co_u32_e32 v21, vcc, 0, v195, vcc
	v_add_co_u32_e32 v24, vcc, 0x14a20000, v194
	global_load_dwordx4 v[16:19], v[16:17], off
	s_nop 0
	global_load_dwordx4 v[20:23], v[20:21], off
	v_addc_co_u32_e32 v25, vcc, 0, v195, vcc
	v_add_co_u32_e32 v28, vcc, 0x14a30000, v194
	s_nop 1
	v_addc_co_u32_e32 v29, vcc, 0, v195, vcc
	v_add_co_u32_e32 v32, vcc, 0x17a00000, v194
	global_load_dwordx4 v[24:27], v[24:25], off
	s_nop 0
	global_load_dwordx4 v[28:31], v[28:29], off
	v_addc_co_u32_e32 v33, vcc, 0, v195, vcc
	v_add_co_u32_e32 v36, vcc, 0x17a10000, v194
	s_nop 1
	v_addc_co_u32_e32 v37, vcc, 0, v195, vcc
	v_add_co_u32_e32 v40, vcc, 0x17a20000, v194
	global_load_dwordx4 v[32:35], v[32:33], off
	s_nop 0
	global_load_dwordx4 v[36:39], v[36:37], off
	v_addc_co_u32_e32 v41, vcc, 0, v195, vcc
	v_add_co_u32_e32 v42, vcc, 0x17a30000, v194
	s_nop 1
	v_addc_co_u32_e32 v43, vcc, 0, v195, vcc
	global_load_dwordx4 v[134:137], v[40:41], off
	global_load_dwordx4 v[138:141], v[42:43], off
	v_add_co_u32_e32 v40, vcc, 0x14a40000, v194
	s_nop 1
	v_addc_co_u32_e32 v41, vcc, 0, v195, vcc
	v_add_co_u32_e32 v44, vcc, 0x14a50000, v194
	s_nop 1
	v_addc_co_u32_e32 v45, vcc, 0, v195, vcc
	v_add_co_u32_e32 v48, vcc, 0x14a60000, v194
	global_load_dwordx4 v[40:43], v[40:41], off
	s_nop 0
	global_load_dwordx4 v[44:47], v[44:45], off
	v_addc_co_u32_e32 v49, vcc, 0, v195, vcc
	v_add_co_u32_e32 v52, vcc, 0x14a70000, v194
	s_nop 1
	v_addc_co_u32_e32 v53, vcc, 0, v195, vcc
	v_add_co_u32_e32 v56, vcc, 0x17a40000, v194
	global_load_dwordx4 v[48:51], v[48:49], off
	s_nop 0
	global_load_dwordx4 v[52:55], v[52:53], off
	v_addc_co_u32_e32 v57, vcc, 0, v195, vcc
	v_add_co_u32_e32 v58, vcc, 0x17a50000, v194
	s_nop 1
	v_addc_co_u32_e32 v59, vcc, 0, v195, vcc
	global_load_dwordx4 v[158:161], v[56:57], off
	global_load_dwordx4 v[162:165], v[58:59], off
	v_add_co_u32_e32 v56, vcc, 0x17a60000, v194
	s_nop 1
	v_addc_co_u32_e32 v57, vcc, 0, v195, vcc
	v_add_co_u32_e32 v58, vcc, 0x17a70000, v194
	s_nop 1
	v_addc_co_u32_e32 v59, vcc, 0, v195, vcc
	global_load_dwordx4 v[150:153], v[56:57], off
	global_load_dwordx4 v[154:157], v[58:59], off
	v_add_co_u32_e32 v56, vcc, 0x14a80000, v194
	s_nop 1
	v_addc_co_u32_e32 v57, vcc, 0, v195, vcc
	v_add_co_u32_e32 v58, vcc, 0x14a90000, v194
	s_nop 1
	v_addc_co_u32_e32 v59, vcc, 0, v195, vcc
	global_load_dwordx4 v[80:83], v[56:57], off
	global_load_dwordx4 v[84:87], v[58:59], off
	v_add_co_u32_e32 v56, vcc, 0x14aa0000, v194
	s_nop 1
	v_addc_co_u32_e32 v57, vcc, 0, v195, vcc
	v_add_co_u32_e32 v58, vcc, 0x14ab0000, v194
	s_nop 1
	v_addc_co_u32_e32 v59, vcc, 0, v195, vcc
	global_load_dwordx4 v[88:91], v[56:57], off
	global_load_dwordx4 v[92:95], v[58:59], off
	v_add_co_u32_e32 v56, vcc, 0x17a80000, v194
	s_nop 1
	v_addc_co_u32_e32 v57, vcc, 0, v195, vcc
	v_add_co_u32_e32 v58, vcc, 0x17a90000, v194
	s_nop 1
	v_addc_co_u32_e32 v59, vcc, 0, v195, vcc
	global_load_dwordx4 v[126:129], v[56:57], off
	global_load_dwordx4 v[130:133], v[58:59], off
	v_add_co_u32_e32 v56, vcc, 0x17aa0000, v194
	s_nop 1
	v_addc_co_u32_e32 v57, vcc, 0, v195, vcc
	v_add_co_u32_e32 v58, vcc, 0x17ab0000, v194
	s_nop 1
	v_addc_co_u32_e32 v59, vcc, 0, v195, vcc
	global_load_dwordx4 v[114:117], v[56:57], off
	global_load_dwordx4 v[118:121], v[58:59], off
	s_waitcnt vmcnt(23)
	ds_write_b128 v220, v[16:19]
	s_waitcnt vmcnt(22)
	ds_write_b128 v221, v[20:23]
	s_waitcnt vmcnt(21)
	ds_write_b128 v222, v[24:27]
	s_waitcnt vmcnt(20)
	ds_write_b128 v223, v[28:31]
	v_add_u32_e32 v229, s33, v205
	ds_read_b128 v[56:59], v229
	v_add_u32_e32 v227, s33, v207
	v_add_u32_e32 v112, s33, v209
	v_add_u32_e32 v228, s33, v211
	v_cmp_lt_i32_e64 s[94:95], 0, v248
	v_mov_b64_e32 v[124:125], s[86:87]
	v_mov_b64_e32 v[122:123], s[84:85]
	s_waitcnt lgkmcnt(0)
	v_mfma_f32_32x32x16_bf16 v[16:31], v[56:59], v[108:111], v[0:15]
	ds_read_b128 v[56:59], v227
	s_mov_b32 s93, 0x14ac0000
	s_waitcnt lgkmcnt(0)
	v_mfma_f32_32x32x16_bf16 v[16:31], v[56:59], v[104:107], v[16:31]
	ds_read_b128 v[56:59], v112
	s_waitcnt lgkmcnt(0)
	v_mfma_f32_32x32x16_bf16 v[16:31], v[56:59], v[100:103], v[16:31]
	ds_read_b128 v[56:59], v228
	s_waitcnt vmcnt(15)
	ds_write_b128 v220, v[40:43]
	s_waitcnt vmcnt(14)
	ds_write_b128 v221, v[44:47]
	s_waitcnt vmcnt(13)
	ds_write_b128 v222, v[48:51]
	s_waitcnt vmcnt(12)
	ds_write_b128 v223, v[52:55]
	ds_read_b128 v[40:43], v229
	s_waitcnt lgkmcnt(5)
	v_mfma_f32_32x32x16_bf16 v[16:31], v[56:59], v[96:99], v[16:31]
	s_waitcnt lgkmcnt(0)
	v_mfma_f32_32x32x16_bf16 v[64:79], v[40:43], v[108:111], v[0:15]
	s_nop 9
	v_exp_f32_e32 v16, v16
	v_exp_f32_e32 v17, v17
	v_exp_f32_e32 v18, v18
	v_exp_f32_e32 v19, v19
	v_cndmask_b32_e64 v16, v16, 0, s[94:95]
	v_cmp_lt_i32_e64 s[94:95], 1, v248
	v_exp_f32_e32 v20, v20
	v_exp_f32_e32 v21, v21
	v_cndmask_b32_e64 v17, v17, 0, s[94:95]
	v_cmp_lt_i32_e64 s[94:95], 2, v248
	ds_read_b128 v[40:43], v227
	v_exp_f32_e32 v22, v22
	v_cndmask_b32_e64 v18, v18, 0, s[94:95]
	v_cmp_lt_i32_e64 s[94:95], 3, v248
	v_exp_f32_e32 v23, v23
	v_exp_f32_e32 v24, v24
	v_cndmask_b32_e64 v19, v19, 0, s[94:95]
	v_cmp_lt_i32_e64 s[94:95], 8, v248
	s_waitcnt lgkmcnt(0)
; #define STAGE_K_D(T) { _Pragma("unroll") for (int j = 0; j < ((T) == 4 ? 1 : 4); ++j) *(LAS bf16x8*)(kwv + (8 * j + vkey) * 128 + ((vchunk ^ ST_SW(8 * j + vkey)) << 4)) = kb[(T) % 3][j]; }
; template <int MIX, bool DRY = false>
; __device__ __forceinline__ void attn_phase(LAS unsigned char* lds, const bf16_t* Qb, const bf16_t* Kb, const bf16_t* Vb, bf16_t* Gb, const float* qg, const float* kg, const float* sinks) {
;     ...
;                 for (int kt = 0; kt < 5; ++kt) {
;                     const int kf0 = f0 - 128 + 32 * kt;
;                     if (kt < 4) { STAGE_K_D(kt + 1) ATT_QK(S2[(kt + 1) & 1], GETK_D) }
;     ...
;                     ATT_SMPV(kt, S2[kt & 1], kf0, qi, md, GETV_D, true, true, true)
;                     if (kt + 3 < 5) {
; #pragma unroll
;                         for (int s = 0; s < (kt + 3 == 4 ? 1 : 4); ++s) kb[kt % 3][s] = *(const bf16x8*)(kp + (kt + 3) * kstep + s * vstep8);
; #pragma unroll
;                         for (int j = 0; j < (kt + 3 == 4 ? 1 : 4); ++j) vb[kt % 3][j] = *(const u32x4*)(vp + (kt + 3) * kstep + j * vstep8);
;                     }
;                     __builtin_amdgcn_sched_barrier(0);
	v_mfma_f32_32x32x16_bf16 v[64:79], v[40:43], v[104:107], v[64:79]
	ds_read_b128 v[40:43], v112
	v_cndmask_b32_e64 v20, v20, 0, s[94:95]
	v_cmp_lt_i32_e64 s[94:95], 9, v248
	s_nop 1
	v_cndmask_b32_e64 v21, v21, 0, s[94:95]
	v_cmp_lt_i32_e64 s[94:95], 10, v248
	s_waitcnt lgkmcnt(0)
	v_mfma_f32_32x32x16_bf16 v[64:79], v[40:43], v[100:103], v[64:79]
	ds_read_b128 v[40:43], v228
	v_cndmask_b32_e64 v22, v22, 0, s[94:95]
	v_cmp_lt_i32_e64 s[94:95], 11, v248
	ds_write_b128 v224, v[32:35] offset:4096
	ds_write_b128 v224, v[36:39] offset:5248
	v_cndmask_b32_e64 v23, v23, 0, s[94:95]
	v_cmp_lt_i32_e64 s[94:95], 16, v248
	s_waitcnt lgkmcnt(2)
	v_mfma_f32_32x32x16_bf16 v[64:79], v[40:43], v[96:99], v[64:79]
	v_cndmask_b32_e64 v142, v24, 0, s[94:95]
	v_exp_f32_e32 v24, v25
	v_cmp_lt_i32_e64 s[94:95], 17, v248
	v_cvt_pk_bf16_f32 v40, v16, v17
	v_cvt_pk_bf16_f32 v41, v18, v19
	v_cndmask_b32_e64 v143, v24, 0, s[94:95]
	v_exp_f32_e32 v24, v26
	v_cmp_lt_i32_e64 s[94:95], 18, v248
	v_cvt_pk_bf16_f32 v42, v20, v21
	v_cvt_pk_bf16_f32 v43, v22, v23
	v_cndmask_b32_e64 v144, v24, 0, s[94:95]
	v_exp_f32_e32 v24, v27
	v_cmp_lt_i32_e64 s[94:95], 19, v248
	ds_read_b64_tr_b16 v[16:17], v225 offset:4096
	ds_read_b64_tr_b16 v[18:19], v225 offset:5248
	ds_read_b64_tr_b16 v[20:21], v225 offset:4160
	ds_read_b64_tr_b16 v[22:23], v225 offset:5312
	v_cndmask_b32_e64 v145, v24, 0, s[94:95]
	v_exp_f32_e32 v24, v28
	v_cmp_lt_i32_e64 s[94:95], 24, v248
	s_waitcnt lgkmcnt(2)
	v_mfma_f32_32x32x16_bf16 v[48:63], v[16:19], v[40:43], 0
	ds_write_b128 v224, v[134:137] offset:4096
	ds_write_b128 v224, v[138:141] offset:5248
	v_cndmask_b32_e64 v146, v24, 0, s[94:95]
	v_exp_f32_e32 v24, v29
	v_cmp_lt_i32_e64 s[94:95], 25, v248
	ds_read_b64_tr_b16 v[134:135], v225 offset:4096
	ds_read_b64_tr_b16 v[136:137], v225 offset:5248
	ds_read_b64_tr_b16 v[138:139], v225 offset:4160
	ds_read_b64_tr_b16 v[140:141], v225 offset:5312
	v_cndmask_b32_e64 v147, v24, 0, s[94:95]
	v_exp_f32_e32 v24, v30
	v_cmp_lt_i32_e64 s[94:95], 26, v248
	v_cvt_pk_bf16_f32 v142, v142, v143
	v_cvt_pk_bf16_f32 v143, v144, v145
	v_cndmask_b32_e64 v148, v24, 0, s[94:95]
	v_exp_f32_e32 v24, v31
	v_cmp_lt_i32_e64 s[94:95], 27, v248
	v_cvt_pk_bf16_f32 v144, v146, v147
	s_nop 0
	v_cndmask_b32_e64 v149, v24, 0, s[94:95]
	v_cvt_pk_bf16_f32 v145, v148, v149
	s_waitcnt lgkmcnt(6)
	v_mfma_f32_32x32x16_bf16 v[16:31], v[20:23], v[40:43], 0
	s_waitcnt lgkmcnt(2)
	v_mfma_f32_32x32x16_bf16 v[48:63], v[134:137], v[142:145], v[48:63]
	v_add_co_u32_e32 v134, vcc, s93, v194
	s_mov_b32 s93, 0x14ad0000
	s_nop 0
	v_addc_co_u32_e32 v135, vcc, 0, v195, vcc
	global_load_dwordx4 v[166:169], v[134:135], off
	v_add_co_u32_e32 v134, vcc, s93, v194
	v_mfma_f32_32x32x16_bf16 v[32:47], v[122:125], v[40:43], 0
	s_nop 0
	v_addc_co_u32_e32 v135, vcc, 0, v195, vcc
	s_mov_b32 s93, 0x14ae0000
	global_load_dwordx4 v[170:173], v[134:135], off
	v_add_co_u32_e32 v134, vcc, s93, v194
	s_mov_b32 s93, 0x14af0000
	s_nop 0
	v_addc_co_u32_e32 v135, vcc, 0, v195, vcc
	global_load_dwordx4 v[174:177], v[134:135], off
	v_add_co_u32_e32 v134, vcc, s93, v194
	s_mov_b32 s93, 0x17ac0000
	s_nop 0
	v_addc_co_u32_e32 v135, vcc, 0, v195, vcc
	global_load_dwordx4 v[178:181], v[134:135], off
	v_add_co_u32_e32 v134, vcc, s93, v194
	s_mov_b32 s93, 0x17ad0000
	s_nop 0
	v_addc_co_u32_e32 v135, vcc, 0, v195, vcc
	s_waitcnt lgkmcnt(0)
	v_mfma_f32_32x32x16_bf16 v[16:31], v[138:141], v[142:145], v[16:31]
	v_mfma_f32_32x32x16_bf16 v[32:47], v[122:125], v[142:145], v[32:47]
	global_load_dwordx4 v[142:145], v[134:135], off
	v_add_co_u32_e32 v134, vcc, s93, v194
	s_mov_b32 s93, 0x17ae0000
	s_nop 0
	v_addc_co_u32_e32 v135, vcc, 0, v195, vcc
	global_load_dwordx4 v[146:149], v[134:135], off
	v_add_co_u32_e32 v134, vcc, s93, v194
	s_mov_b32 s93, 0x17af0000
	s_nop 0
	v_addc_co_u32_e32 v135, vcc, 0, v195, vcc
	v_add_co_u32_e32 v138, vcc, s93, v194
	global_load_dwordx4 v[134:137], v[134:135], off
	s_nop 0
	v_addc_co_u32_e32 v139, vcc, 0, v195, vcc
	global_load_dwordx4 v[138:141], v[138:139], off
	s_waitcnt vmcnt(15)
	ds_write_b128 v220, v[80:83]
	s_waitcnt vmcnt(14)
	ds_write_b128 v221, v[84:87]
	s_waitcnt vmcnt(13)
	ds_write_b128 v222, v[88:91]
	s_waitcnt vmcnt(12)
	ds_write_b128 v223, v[92:95]
	ds_read_b128 v[230:233], v229
	v_exp_f32_e32 v64, v64
	v_exp_f32_e32 v65, v65
	v_cmp_lt_i32_e64 s[94:95], 0, v249
	v_exp_f32_e32 v66, v66
	v_exp_f32_e32 v67, v67
	v_cndmask_b32_e64 v64, v64, 0, s[94:95]
	s_waitcnt lgkmcnt(0)
	v_mfma_f32_32x32x16_bf16 v[80:95], v[230:233], v[108:111], v[0:15]
	ds_read_b128 v[230:233], v227
	v_cmp_lt_i32_e64 s[94:95], 1, v249
	v_exp_f32_e32 v68, v68
	v_exp_f32_e32 v69, v69
	v_cndmask_b32_e64 v65, v65, 0, s[94:95]
	v_cmp_lt_i32_e64 s[94:95], 2, v249
	v_exp_f32_e32 v70, v70
	s_waitcnt lgkmcnt(0)
	v_mfma_f32_32x32x16_bf16 v[80:95], v[230:233], v[104:107], v[80:95]
	ds_read_b128 v[230:233], v112
	v_cndmask_b32_e64 v66, v66, 0, s[94:95]
	v_cmp_lt_i32_e64 s[94:95], 3, v249
	v_exp_f32_e32 v71, v71
	v_exp_f32_e32 v72, v72
	v_cndmask_b32_e64 v67, v67, 0, s[94:95]
	s_waitcnt lgkmcnt(0)
	v_mfma_f32_32x32x16_bf16 v[80:95], v[230:233], v[100:103], v[80:95]
	ds_read_b128 v[230:233], v228
	v_cmp_lt_i32_e64 s[94:95], 8, v249
	ds_write_b128 v224, v[158:161] offset:4096
	ds_write_b128 v224, v[162:165] offset:5248
	v_cndmask_b32_e64 v68, v68, 0, s[94:95]
	v_cmp_lt_i32_e64 s[94:95], 9, v249
	v_cvt_pk_bf16_f32 v64, v64, v65
	s_waitcnt lgkmcnt(2)
; #define STAGE_K_D(T) { _Pragma("unroll") for (int j = 0; j < ((T) == 4 ? 1 : 4); ++j) *(LAS bf16x8*)(kwv + (8 * j + vkey) * 128 + ((vchunk ^ ST_SW(8 * j + vkey)) << 4)) = kb[(T) % 3][j]; }
; template <int MIX, bool DRY = false>
; __device__ __forceinline__ void attn_phase(LAS unsigned char* lds, const bf16_t* Qb, const bf16_t* Kb, const bf16_t* Vb, bf16_t* Gb, const float* qg, const float* kg, const float* sinks) {
;     ...
;                 for (int kt = 0; kt < 5; ++kt) {
;                     const int kf0 = f0 - 128 + 32 * kt;
;                     if (kt < 4) { STAGE_K_D(kt + 1) ATT_QK(S2[(kt + 1) & 1], GETK_D) }
;     ...
;                     ATT_SMPV(kt, S2[kt & 1], kf0, qi, md, GETV_D, true, true, true)
;                     if (kt + 3 < 5) {
; #pragma unroll
;                         for (int s = 0; s < (kt + 3 == 4 ? 1 : 4); ++s) kb[kt % 3][s] = *(const bf16x8*)(kp + (kt + 3) * kstep + s * vstep8);
; #pragma unroll
;                         for (int j = 0; j < (kt + 3 == 4 ? 1 : 4); ++j) vb[kt % 3][j] = *(const u32x4*)(vp + (kt + 3) * kstep + j * vstep8);
;                     }
;                     __builtin_amdgcn_sched_barrier(0);
	v_mfma_f32_32x32x16_bf16 v[80:95], v[230:233], v[96:99], v[80:95]
	v_cndmask_b32_e64 v69, v69, 0, s[94:95]
	v_cmp_lt_i32_e64 s[94:95], 10, v249
	v_cvt_pk_bf16_f32 v65, v66, v67
	v_cvt_pk_bf16_f32 v66, v68, v69
	v_cndmask_b32_e64 v70, v70, 0, s[94:95]
	v_cmp_lt_i32_e64 s[94:95], 11, v249
	s_mov_b32 s93, 0x14b00000
	s_nop 0
	v_cndmask_b32_e64 v71, v71, 0, s[94:95]
	v_cmp_lt_i32_e64 s[94:95], 16, v249
	v_cvt_pk_bf16_f32 v67, v70, v71
	s_nop 0
	v_cndmask_b32_e64 v230, v72, 0, s[94:95]
	v_exp_f32_e32 v72, v73
	v_cmp_lt_i32_e64 s[94:95], 17, v249
	v_mfma_f32_32x32x16_bf16 v[32:47], v[122:125], v[64:67], v[32:47]
	s_nop 0
	v_cndmask_b32_e64 v231, v72, 0, s[94:95]
	v_exp_f32_e32 v72, v74
	v_cmp_lt_i32_e64 s[94:95], 18, v249
	s_nop 1
	v_cndmask_b32_e64 v232, v72, 0, s[94:95]
	v_exp_f32_e32 v72, v75
	v_cmp_lt_i32_e64 s[94:95], 19, v249
	s_nop 1
	v_cndmask_b32_e64 v233, v72, 0, s[94:95]
	v_exp_f32_e32 v72, v76
	s_nop 0
	v_cndmask_b32_e64 v76, v72, 0, s[96:97]
	v_exp_f32_e32 v72, v77
	s_nop 0
	v_cndmask_b32_e64 v77, v72, 0, s[98:99]
	v_exp_f32_e32 v72, v78
	s_nop 0
	v_cndmask_b32_e64 v78, v72, 0, s[80:81]
	v_exp_f32_e32 v72, v79
	s_nop 0
	v_cndmask_b32_e64 v79, v72, 0, s[4:5]
	ds_read_b64_tr_b16 v[68:69], v225 offset:4096
	ds_read_b64_tr_b16 v[70:71], v225 offset:5248
	ds_read_b64_tr_b16 v[72:73], v225 offset:4160
	ds_read_b64_tr_b16 v[74:75], v225 offset:5312
	s_waitcnt lgkmcnt(2)
	v_mfma_f32_32x32x16_bf16 v[48:63], v[68:71], v[64:67], v[48:63]
	ds_write_b128 v224, v[150:153] offset:4096
	ds_write_b128 v224, v[154:157] offset:5248
	s_waitcnt lgkmcnt(2)
	v_mfma_f32_32x32x16_bf16 v[16:31], v[72:75], v[64:67], v[16:31]
	ds_read_b64_tr_b16 v[68:69], v225 offset:4096
	ds_read_b64_tr_b16 v[70:71], v225 offset:5248
	ds_read_b64_tr_b16 v[72:73], v225 offset:4160
	ds_read_b64_tr_b16 v[74:75], v225 offset:5312
	v_cvt_pk_bf16_f32 v64, v230, v231
	v_cvt_pk_bf16_f32 v65, v232, v233
	v_cvt_pk_bf16_f32 v66, v76, v77
	v_cvt_pk_bf16_f32 v67, v78, v79
	s_waitcnt lgkmcnt(2)
	s_nop 0
	v_mfma_f32_32x32x16_bf16 v[48:63], v[68:71], v[64:67], v[48:63]
	s_waitcnt lgkmcnt(0)
	v_mfma_f32_32x32x16_bf16 v[16:31], v[72:75], v[64:67], v[16:31]
	v_mfma_f32_32x32x16_bf16 v[32:47], v[122:125], v[64:67], v[32:47]
	v_add_co_u32_e32 v64, vcc, s93, v194
	s_mov_b32 s93, 0x17b00000
	s_nop 0
	v_addc_co_u32_e32 v65, vcc, 0, v195, vcc
	global_load_dwordx4 v[154:157], v[64:65], off
	v_add_co_u32_e32 v64, vcc, s93, v194
	s_nop 1
	v_addc_co_u32_e32 v65, vcc, 0, v195, vcc
	global_load_dwordx4 v[150:153], v[64:65], off
	s_waitcnt vmcnt(9)
	ds_write_b128 v220, v[166:169]
	s_waitcnt vmcnt(8)
	ds_write_b128 v221, v[170:173]
	s_waitcnt vmcnt(7)
	ds_write_b128 v222, v[174:177]
	s_waitcnt vmcnt(6)
	ds_write_b128 v223, v[178:181]
	ds_read_b128 v[158:161], v229
	v_exp_f32_e32 v88, v88
	v_exp_f32_e32 v80, v80
	v_exp_f32_e32 v81, v81
	v_exp_f32_e32 v82, v82
	v_exp_f32_e32 v83, v83
	v_exp_f32_e32 v84, v84
	v_exp_f32_e32 v85, v85
	v_exp_f32_e32 v86, v86
	s_waitcnt lgkmcnt(0)
	v_mfma_f32_32x32x16_bf16 v[64:79], v[158:161], v[108:111], v[0:15]
	ds_read_b128 v[158:161], v227
	v_exp_f32_e32 v87, v87
	v_cndmask_b32_e64 v80, v80, 0, s[6:7]
	v_cndmask_b32_e64 v81, v81, 0, s[8:9]
	v_cndmask_b32_e64 v82, v82, 0, s[10:11]
	v_cndmask_b32_e64 v83, v83, 0, s[12:13]
	v_cndmask_b32_e64 v84, v84, 0, s[14:15]
	v_cndmask_b32_e64 v85, v85, 0, s[16:17]
	s_waitcnt lgkmcnt(0)
	v_mfma_f32_32x32x16_bf16 v[64:79], v[158:161], v[104:107], v[64:79]
	ds_read_b128 v[158:161], v112
	v_cndmask_b32_e64 v86, v86, 0, s[18:19]
	v_cndmask_b32_e64 v87, v87, 0, s[20:21]
	v_cvt_pk_bf16_f32 v80, v80, v81
	v_cvt_pk_bf16_f32 v81, v82, v83
	v_cvt_pk_bf16_f32 v82, v84, v85
	v_cvt_pk_bf16_f32 v83, v86, v87
	s_waitcnt lgkmcnt(0)
	v_mfma_f32_32x32x16_bf16 v[64:79], v[158:161], v[100:103], v[64:79]
	ds_read_b128 v[158:161], v228
	ds_write_b128 v224, v[126:129] offset:4096
	ds_write_b128 v224, v[130:133] offset:5248
	s_waitcnt lgkmcnt(2)
	v_mfma_f32_32x32x16_bf16 v[64:79], v[158:161], v[96:99], v[64:79]
	v_cndmask_b32_e64 v158, v88, 0, s[22:23]
	v_exp_f32_e32 v88, v89
	s_nop 0
	v_cndmask_b32_e64 v159, v88, 0, s[24:25]
	v_exp_f32_e32 v88, v90
	v_mfma_f32_32x32x16_bf16 v[32:47], v[122:125], v[80:83], v[32:47]
	v_cndmask_b32_e64 v160, v88, 0, s[26:27]
	v_exp_f32_e32 v88, v91
	s_nop 0
	v_cndmask_b32_e64 v161, v88, 0, s[28:29]
	v_exp_f32_e32 v88, v92
	s_nop 0
	v_cndmask_b32_e64 v92, v88, 0, s[30:31]
	v_exp_f32_e32 v88, v93
	s_nop 0
	v_cndmask_b32_e64 v93, v88, 0, s[34:35]
	v_exp_f32_e32 v88, v94
	s_nop 0
	v_cndmask_b32_e64 v94, v88, 0, s[0:1]
	v_exp_f32_e32 v88, v95
	s_nop 0
	v_cndmask_b32_e64 v95, v88, 0, s[36:37]
	ds_read_b64_tr_b16 v[84:85], v225 offset:4096
	ds_read_b64_tr_b16 v[86:87], v225 offset:5248
	ds_read_b64_tr_b16 v[88:89], v225 offset:4160
	ds_read_b64_tr_b16 v[90:91], v225 offset:5312
	s_waitcnt lgkmcnt(2)
	v_mfma_f32_32x32x16_bf16 v[48:63], v[84:87], v[80:83], v[48:63]
	ds_write_b128 v224, v[114:117] offset:4096
	ds_write_b128 v224, v[118:121] offset:5248
	s_waitcnt lgkmcnt(2)
	v_mfma_f32_32x32x16_bf16 v[16:31], v[88:91], v[80:83], v[16:31]
	v_cvt_pk_bf16_f32 v80, v158, v159
	v_cvt_pk_bf16_f32 v81, v160, v161
	v_cvt_pk_bf16_f32 v82, v92, v93
	v_cvt_pk_bf16_f32 v83, v94, v95
	ds_read_b64_tr_b16 v[84:85], v225 offset:4096
	ds_read_b64_tr_b16 v[86:87], v225 offset:5248
	ds_read_b64_tr_b16 v[88:89], v225 offset:4160
	ds_read_b64_tr_b16 v[90:91], v225 offset:5312
	v_mfma_f32_32x32x16_bf16 v[32:47], v[122:125], v[80:83], v[32:47]
	s_waitcnt lgkmcnt(2)
	v_mfma_f32_32x32x16_bf16 v[48:63], v[84:87], v[80:83], v[48:63]
	s_waitcnt lgkmcnt(0)
	v_mfma_f32_32x32x16_bf16 v[16:31], v[88:91], v[80:83], v[16:31]
	s_waitcnt vmcnt(1)
; #define LAS __attribute__((address_space(3)))
; #define STAGE_K_D(T) { _Pragma("unroll") for (int j = 0; j < ((T) == 4 ? 1 : 4); ++j) *(LAS bf16x8*)(kwv + (8 * j + vkey) * 128 + ((vchunk ^ ST_SW(8 * j + vkey)) << 4)) = kb[(T) % 3][j]; }
; template <int MIX, bool DRY = false>
; __device__ __forceinline__ void attn_phase(LAS unsigned char* lds, const bf16_t* Qb, const bf16_t* Kb, const bf16_t* Vb, bf16_t* Gb, const float* qg, const float* kg, const float* sinks) {
;     ...
;                 for (int kt = 0; kt < 5; ++kt) {
;                     const int kf0 = f0 - 128 + 32 * kt;
;                     if (kt < 4) { STAGE_K_D(kt + 1) ATT_QK(S2[(kt + 1) & 1], GETK_D) }
;     ...
;                     ATT_SMPV(kt, S2[kt & 1], kf0, qi, md, GETV_D, true, true, true)
;                     if (kt + 3 < 5) {
; #pragma unroll
;                         for (int s = 0; s < (kt + 3 == 4 ? 1 : 4); ++s) kb[kt % 3][s] = *(const bf16x8*)(kp + (kt + 3) * kstep + s * vstep8);
; #pragma unroll
;                         for (int j = 0; j < (kt + 3 == 4 ? 1 : 4); ++j) vb[kt % 3][j] = *(const u32x4*)(vp + (kt + 3) * kstep + j * vstep8);
;                     }
;                     __builtin_amdgcn_sched_barrier(0);
;                 }
;                 const float lsum = Lr[0];
;                 const int row = hr * CT + tl, f = ((tl >> 1) ^ (tl >> 4) ^ (hr << 2)) & 15;
;                 LAS unsigned char* orow = Oacc + row * 128;
; #pragma unroll
;                 for (int gq = 0; gq < 4; ++gq) {
;                     LAS u32x2* p0 = (LAS u32x2*)(orow + (((2 * gq + h) ^ f) << 3)); LAS u32x2* p1 = (LAS u32x2*)(orow + (((8 + 2 * gq + h) ^ f) << 3));
;                     const u32x2 x = *p0, y = *p1;
	ds_write_b128 v220, v[154:157]
	ds_read_b128 v[114:117], v229
	v_exp_f32_e32 v118, v64
	v_exp_f32_e32 v119, v65
	v_exp_f32_e32 v120, v66
	v_exp_f32_e32 v121, v67
	ds_read_b128 v[64:67], v227
	v_exp_f32_e32 v126, v68
	v_exp_f32_e32 v72, v72
	s_waitcnt lgkmcnt(1)
	v_mfma_f32_32x32x16_bf16 v[80:95], v[114:117], v[108:111], v[0:15]
	v_exp_f32_e32 v114, v69
	v_exp_f32_e32 v115, v70
	v_exp_f32_e32 v116, v71
	ds_read_b128 v[68:71], v228
	ds_read_b128 v[108:111], v112
	v_exp_f32_e32 v117, v73
	ds_write_b128 v224, v[142:145] offset:4096
	ds_write_b128 v224, v[146:149] offset:5248
	v_cndmask_b32_e64 v73, v118, 0, s[40:41]
	s_waitcnt lgkmcnt(4)
	v_mfma_f32_32x32x16_bf16 v[80:95], v[64:67], v[104:107], v[80:95]
	v_exp_f32_e32 v104, v74
	v_exp_f32_e32 v105, v75
	v_cndmask_b32_e64 v74, v119, 0, s[42:43]
	v_cndmask_b32_e64 v75, v120, 0, s[44:45]
	ds_read_b64_tr_b16 v[64:65], v225 offset:4096
	ds_read_b64_tr_b16 v[66:67], v225 offset:5248
	v_cndmask_b32_e64 v106, v116, 0, s[54:55]
	s_waitcnt lgkmcnt(4)
	v_mfma_f32_32x32x16_bf16 v[80:95], v[108:111], v[100:103], v[80:95]
	v_cndmask_b32_e64 v100, v121, 0, s[46:47]
	v_cndmask_b32_e64 v101, v126, 0, s[48:49]
	v_cndmask_b32_e64 v102, v114, 0, s[50:51]
	v_cndmask_b32_e64 v103, v115, 0, s[52:53]
	v_mfma_f32_32x32x16_bf16 v[80:95], v[68:71], v[96:99], v[80:95]
	v_cvt_pk_bf16_f32 v68, v73, v74
	v_cvt_pk_bf16_f32 v69, v75, v100
	v_cvt_pk_bf16_f32 v70, v101, v102
	v_cvt_pk_bf16_f32 v71, v103, v106
	s_nop 1
	v_mfma_f32_32x32x16_bf16 v[32:47], v[122:125], v[68:71], v[32:47]
	s_nop 4
	v_cndmask_b32_e64 v84, v72, 0, s[56:57]
	ds_read_b64_tr_b16 v[74:75], v225 offset:5312
	ds_read_b64_tr_b16 v[72:73], v225 offset:4160
	v_cndmask_b32_e64 v85, v117, 0, s[58:59]
	v_cndmask_b32_e64 v86, v104, 0, s[60:61]
	ds_write_b128 v224, v[134:137] offset:4096
	ds_write_b128 v224, v[138:141] offset:5248
	s_waitcnt lgkmcnt(4)
	v_mfma_f32_32x32x16_bf16 v[48:63], v[64:67], v[68:71], v[48:63]
	v_exp_f32_e32 v64, v76
	v_exp_f32_e32 v65, v77
	v_exp_f32_e32 v66, v78
	v_cndmask_b32_e64 v76, v105, 0, s[62:63]
	v_cndmask_b32_e64 v77, v64, 0, s[64:65]
	s_waitcnt lgkmcnt(2)
	v_mfma_f32_32x32x16_bf16 v[16:31], v[72:75], v[68:71], v[16:31]
	v_exp_f32_e32 v74, v79
	v_cndmask_b32_e64 v72, v65, 0, s[66:67]
	v_cndmask_b32_e64 v73, v66, 0, s[68:69]
	v_cvt_pk_bf16_f32 v68, v84, v85
	v_cndmask_b32_e64 v71, v74, 0, s[70:71]
	v_cvt_pk_bf16_f32 v69, v86, v76
	v_cvt_pk_bf16_f32 v70, v77, v72
	v_cvt_pk_bf16_f32 v71, v73, v71
	ds_read_b64_tr_b16 v[64:65], v225 offset:4096
	ds_read_b64_tr_b16 v[66:67], v225 offset:5248
	v_mfma_f32_32x32x16_bf16 v[32:47], v[122:125], v[68:71], v[32:47]
	ds_read_b64_tr_b16 v[74:75], v225 offset:5312
	ds_read_b64_tr_b16 v[72:73], v225 offset:4160
	s_waitcnt lgkmcnt(2)
	v_mfma_f32_32x32x16_bf16 v[48:63], v[64:67], v[68:71], v[48:63]
	s_waitcnt lgkmcnt(0)
	v_mfma_f32_32x32x16_bf16 v[16:31], v[72:75], v[68:71], v[16:31]
	v_exp_f32_e32 v64, v82
	v_exp_f32_e32 v68, v83
	s_waitcnt vmcnt(0)
	ds_write_b128 v224, v[150:153] offset:4096
	v_exp_f32_e32 v69, v80
	v_exp_f32_e32 v71, v81
	v_cndmask_b32_e64 v70, v64, 0, s[72:73]
	ds_read_b64_tr_b16 v[64:65], v225 offset:4096
	ds_read_b64_tr_b16 v[66:67], v225 offset:5248
	v_cndmask_b32_e64 v68, v68, 0, s[74:75]
	v_cvt_pk_bf16_f32 v111, v70, v68
	v_cndmask_b32_e64 v68, v69, 0, s[76:77]
	v_cndmask_b32_e64 v69, v71, 0, s[78:79]
	v_cvt_pk_bf16_f32 v110, v68, v69
	v_mov_b32_e32 v112, v113
	ds_read_b64_tr_b16 v[68:69], v225 offset:5312
	s_waitcnt lgkmcnt(1)
	v_mfma_f32_32x32x16_bf16 v[48:63], v[64:67], v[110:113], v[48:63]
	ds_read_b64_tr_b16 v[66:67], v225 offset:4160
	v_mfma_f32_32x32x16_bf16 v[32:47], v[122:125], v[110:113], v[32:47]
	s_waitcnt lgkmcnt(0)
	v_mfma_f32_32x32x16_bf16 v[16:31], v[66:69], v[110:113], v[16:31]
	s_nop 9
	v_lshrrev_b32_e32 v33, 1, v226
	v_lshrrev_b32_e32 v34, 4, v226
	v_xor_b32_e32 v33, v33, v34
	v_bitop3_b32 v33, v33, v216, 15 bitop3:0x6c
	v_xor_b32_e32 v34, v33, v204
	v_lshlrev_b32_e32 v34, 3, v34
	v_add3_u32 v40, 0, v34, v219
	v_xor_b32_e32 v34, v33, v212
	v_lshlrev_b32_e32 v34, 3, v34
	v_add3_u32 v41, 0, v34, v219
	ds_read_b64 v[34:35], v40
	ds_read_b64 v[36:37], v41
	s_waitcnt lgkmcnt(1)
; #define LAS __attribute__((address_space(3)))
; __device__ __forceinline__ unsigned pkbf(float lo, float hi) { f32x2v v = {lo, hi}; return __builtin_bit_cast(unsigned, __builtin_convertvector(v, bf2_t)); }
; __device__ __forceinline__ float bflo(unsigned w) { return __uint_as_float(w << 16); }
; __device__ __forceinline__ float bfhi(unsigned w) { return __uint_as_float(w & 0xffff0000u); }
; template <int MIX, bool DRY = false>
; __device__ __forceinline__ void attn_phase(LAS unsigned char* lds, const bf16_t* Qb, const bf16_t* Kb, const bf16_t* Vb, bf16_t* Gb, const float* qg, const float* kg, const float* sinks) {
;     ...
;                 const int row = hr * CT + tl, f = ((tl >> 1) ^ (tl >> 4) ^ (hr << 2)) & 15;
;                 LAS unsigned char* orow = Oacc + row * 128;
; #pragma unroll
;                 for (int gq = 0; gq < 4; ++gq) {
;                     LAS u32x2* p0 = (LAS u32x2*)(orow + (((2 * gq + h) ^ f) << 3)); LAS u32x2* p1 = (LAS u32x2*)(orow + (((8 + 2 * gq + h) ^ f) << 3));
;                     const u32x2 x = *p0, y = *p1;
;                     u32x2 w0, w1; w0.x = pkbf(O0[4 * gq] + bflo(x.x), O0[4 * gq + 1] + bfhi(x.x)); w0.y = pkbf(O0[4 * gq + 2] + bflo(x.y), O0[4 * gq + 3] + bfhi(x.y));
;                     w1.x = pkbf(O1[4 * gq] + bflo(y.x), O1[4 * gq + 1] + bfhi(y.x)); w1.y = pkbf(O1[4 * gq + 2] + bflo(y.y), O1[4 * gq + 3] + bfhi(y.y));
;                     *p0 = w0; *p1 = w1;
;                 }
;                 if (h == 0) lacc[row] += lsum;
	v_lshlrev_b32_e32 v38, 16, v34
	v_and_b32_e32 v39, 0xffff0000, v34
	v_pk_add_f32 v[38:39], v[48:49], v[38:39]
	s_nop 0
	v_cvt_pk_bf16_f32 v34, v38, v39
	v_lshlrev_b32_e32 v38, 16, v35
	v_and_b32_e32 v39, 0xffff0000, v35
	v_pk_add_f32 v[38:39], v[50:51], v[38:39]
	s_nop 0
	v_cvt_pk_bf16_f32 v35, v38, v39
	s_waitcnt lgkmcnt(0)
	v_lshlrev_b32_e32 v38, 16, v36
	v_and_b32_e32 v39, 0xffff0000, v36
	v_pk_add_f32 v[16:17], v[16:17], v[38:39]
	v_lshlrev_b32_e32 v36, 16, v37
	v_and_b32_e32 v37, 0xffff0000, v37
	v_cvt_pk_bf16_f32 v16, v16, v17
	v_pk_add_f32 v[18:19], v[18:19], v[36:37]
	s_nop 0
	v_cvt_pk_bf16_f32 v17, v18, v19
	ds_write_b64 v40, v[34:35]
	ds_write_b64 v41, v[16:17]
	v_xor_b32_e32 v16, v33, v206
	v_lshlrev_b32_e32 v16, 3, v16
	v_add3_u32 v36, 0, v16, v219
	v_xor_b32_e32 v16, v33, v213
	v_lshlrev_b32_e32 v16, 3, v16
	v_add3_u32 v37, 0, v16, v219
	ds_read_b64 v[16:17], v36
	ds_read_b64 v[18:19], v37
	s_waitcnt lgkmcnt(1)
	v_lshlrev_b32_e32 v34, 16, v16
	v_and_b32_e32 v35, 0xffff0000, v16
	v_pk_add_f32 v[34:35], v[52:53], v[34:35]
	s_nop 0
	v_cvt_pk_bf16_f32 v16, v34, v35
	v_lshlrev_b32_e32 v34, 16, v17
	v_and_b32_e32 v35, 0xffff0000, v17
	v_pk_add_f32 v[34:35], v[54:55], v[34:35]
	s_nop 0
	v_cvt_pk_bf16_f32 v17, v34, v35
	s_waitcnt lgkmcnt(0)
	v_lshlrev_b32_e32 v34, 16, v18
	v_and_b32_e32 v35, 0xffff0000, v18
	v_pk_add_f32 v[20:21], v[20:21], v[34:35]
	s_nop 0
	v_cvt_pk_bf16_f32 v18, v20, v21
	v_lshlrev_b32_e32 v20, 16, v19
	v_and_b32_e32 v21, 0xffff0000, v19
	v_pk_add_f32 v[20:21], v[22:23], v[20:21]
	s_nop 0
	v_cvt_pk_bf16_f32 v19, v20, v21
	ds_write_b64 v36, v[16:17]
	ds_write_b64 v37, v[18:19]
	v_xor_b32_e32 v16, v33, v208
	v_lshlrev_b32_e32 v16, 3, v16
	v_add3_u32 v22, 0, v16, v219
	v_xor_b32_e32 v16, v33, v214
	v_lshlrev_b32_e32 v16, 3, v16
	v_add3_u32 v23, 0, v16, v219
	ds_read_b64 v[16:17], v22
	ds_read_b64 v[18:19], v23
	s_waitcnt lgkmcnt(1)
	v_lshlrev_b32_e32 v20, 16, v16
	v_and_b32_e32 v21, 0xffff0000, v16
	v_pk_add_f32 v[20:21], v[56:57], v[20:21]
	s_nop 0
	v_cvt_pk_bf16_f32 v16, v20, v21
	v_lshlrev_b32_e32 v20, 16, v17
	v_and_b32_e32 v21, 0xffff0000, v17
	v_pk_add_f32 v[20:21], v[58:59], v[20:21]
	s_nop 0
	v_cvt_pk_bf16_f32 v17, v20, v21
	s_waitcnt lgkmcnt(0)
	v_lshlrev_b32_e32 v20, 16, v18
	v_and_b32_e32 v21, 0xffff0000, v18
	v_pk_add_f32 v[20:21], v[24:25], v[20:21]
	s_nop 0
	v_cvt_pk_bf16_f32 v18, v20, v21
	v_lshlrev_b32_e32 v20, 16, v19
	v_and_b32_e32 v21, 0xffff0000, v19
	v_pk_add_f32 v[20:21], v[26:27], v[20:21]
	s_nop 0
	v_cvt_pk_bf16_f32 v19, v20, v21
	ds_write_b64 v22, v[16:17]
	ds_write_b64 v23, v[18:19]
	v_xor_b32_e32 v16, v33, v210
	v_lshlrev_b32_e32 v16, 3, v16
	v_add3_u32 v22, 0, v16, v219
	v_xor_b32_e32 v16, v33, v215
	v_lshlrev_b32_e32 v16, 3, v16
	v_add3_u32 v23, 0, v16, v219
	ds_read_b64 v[16:17], v22
	ds_read_b64 v[18:19], v23
	s_waitcnt lgkmcnt(1)
	v_lshlrev_b32_e32 v20, 16, v16
	v_and_b32_e32 v21, 0xffff0000, v16
	v_pk_add_f32 v[20:21], v[60:61], v[20:21]
	s_nop 0
	v_cvt_pk_bf16_f32 v16, v20, v21
	v_lshlrev_b32_e32 v20, 16, v17
	v_and_b32_e32 v21, 0xffff0000, v17
	v_pk_add_f32 v[20:21], v[62:63], v[20:21]
	s_nop 0
	v_cvt_pk_bf16_f32 v17, v20, v21
	s_waitcnt lgkmcnt(0)
	v_lshlrev_b32_e32 v20, 16, v18
	v_and_b32_e32 v21, 0xffff0000, v18
	v_pk_add_f32 v[20:21], v[28:29], v[20:21]
	s_nop 0
	v_cvt_pk_bf16_f32 v18, v20, v21
	v_lshlrev_b32_e32 v20, 16, v19
	v_and_b32_e32 v21, 0xffff0000, v19
	v_pk_add_f32 v[20:21], v[30:31], v[20:21]
	s_nop 0
	v_cvt_pk_bf16_f32 v19, v20, v21
	ds_write_b64 v22, v[16:17]
	ds_write_b64 v23, v[18:19]
	s_and_saveexec_b64 vcc, s[38:39]
	s_cbranch_execz .LBB0_465
	v_add_u32_e32 v16, 0, v218
	ds_read_b32 v17, v16
	s_waitcnt lgkmcnt(0)
	v_add_f32_e32 v17, v32, v17
	ds_write_b32 v16, v17
	s_branch .LBB0_465
